# premix: the loop-invariant token-shift mix vectors are loaded once into free registers instead of per token per column group
# speedup vs baseline: 1.0104x; 1.0024x over previous
.LBB0_285:
	s_waitcnt lgkmcnt(0)
	s_cmp_lt_i32 s2, 4
	s_cselect_b64 s[4:5], -1, 0
	s_cmp_gt_i32 s3, 3
	s_cselect_b64 s[6:7], -1, 0
	s_and_b64 s[4:5], s[4:5], s[6:7]
	s_andn2_b64 vcc, exec, s[4:5]
	s_cbranch_vccnz .LBB0_294
	v_mbcnt_lo_u32_b32 v0, -1, 0
	v_mbcnt_hi_u32_b32 v0, -1, v0
	s_nop 0
	v_add_u32_e32 v1, s95, v0
	s_nop 0
	v_readfirstlane_b32 s4, v1
	s_ashr_i32 s8, s4, 6
	s_lshl_b32 s4, s94, 3
	s_add_i32 s14, s8, s4
	s_cmpk_gt_i32 s14, 0x7ff
	s_cbranch_scc1 .LBB0_294
	s_load_dwordx4 s[4:7], s[0:1], 0x110
	s_load_dwordx2 s[2:3], s[0:1], 0x10
	s_load_dwordx2 s[10:11], s[0:1], 0x30
	v_and_b32_e32 v2, 63, v0
	v_lshlrev_b32_e32 v24, 4, v2
	v_mov_b32_e32 v25, 0
	s_waitcnt lgkmcnt(0)
	v_lshl_add_u64 v[0:1], s[2:3], 0, v[24:25]
	s_mov_b64 s[2:3], 0x1000
	v_lshl_add_u64 v[26:27], v[0:1], 0, s[2:3]
	v_mbcnt_lo_u32_b32 v0, -1, 0
	v_mbcnt_hi_u32_b32 v0, -1, v0
	v_and_b32_e32 v1, 64, v0
	v_add_u32_e32 v1, 64, v1
	v_xor_b32_e32 v3, 1, v0
	v_cmp_lt_i32_e32 vcc, v3, v1
	v_lshl_add_u64 v[28:29], s[4:5], 0, v[24:25]
	v_lshl_add_u64 v[30:31], s[10:11], 0, v[24:25]
	v_cndmask_b32_e32 v3, v0, v3, vcc
	v_lshlrev_b32_e32 v67, 2, v3
	v_xor_b32_e32 v3, 2, v0
	v_cmp_lt_i32_e32 vcc, v3, v1
	s_mov_b64 s[4:5], 0x2000
	v_lshl_add_u64 v[32:33], v[30:31], 0, s[4:5]
	v_cndmask_b32_e32 v3, v0, v3, vcc
	v_lshlrev_b32_e32 v68, 2, v3
	v_xor_b32_e32 v3, 4, v0
	v_cmp_lt_i32_e32 vcc, v3, v1
	s_mov_b64 s[4:5], 0x3000
	v_lshl_add_u64 v[34:35], v[30:31], 0, s[4:5]
	v_cndmask_b32_e32 v3, v0, v3, vcc
	v_lshlrev_b32_e32 v69, 2, v3
	v_xor_b32_e32 v3, 8, v0
	v_cmp_lt_i32_e32 vcc, v3, v1
	s_lshl_b32 s4, s94, 7
	s_lshl_b32 s5, s8, 4
	v_cndmask_b32_e32 v3, v0, v3, vcc
	v_lshlrev_b32_e32 v70, 2, v3
	v_xor_b32_e32 v3, 16, v0
	v_cmp_lt_i32_e32 vcc, v3, v1
	s_add_i32 s4, s4, s5
	s_mov_b64 s[8:9], 0xc00
	v_cndmask_b32_e32 v3, v0, v3, vcc
	v_lshlrev_b32_e32 v71, 2, v3
	v_xor_b32_e32 v3, 32, v0
	v_cmp_lt_i32_e32 vcc, v3, v1
	s_lshl_b32 s15, s96, 3
	s_add_i32 s16, s4, -1
	v_cndmask_b32_e32 v0, v0, v3, vcc
	v_lshlrev_b32_e32 v72, 2, v0
	s_lshl_b32 s17, s96, 7
	v_lshlrev_b32_e32 v24, 3, v2
	v_lshl_add_u64 v[36:37], v[28:29], 0, s[8:9]
	v_mov_b32_e32 v73, 0x358637bd
	s_mov_b32 s18, 0x5c00000
	s_mov_b32 s19, 0xdc00000
	s_mov_b32 s20, 0x11c00000
	global_load_dwordx4 v[112:115], v[30:31], off
	global_load_dwordx4 v[116:119], v[32:33], off
	global_load_dwordx4 v[120:123], v[34:35], off
	global_load_dwordx4 v[124:127], v[30:31], off offset:1024
	global_load_dwordx4 v[128:131], v[32:33], off offset:1024
	global_load_dwordx4 v[132:135], v[34:35], off offset:1024
	global_load_dwordx4 v[136:139], v[30:31], off offset:2048
	global_load_dwordx4 v[140:143], v[32:33], off offset:2048
	global_load_dwordx4 v[144:147], v[34:35], off offset:2048
	global_load_dwordx4 v[148:151], v[30:31], off offset:3072
	global_load_dwordx4 v[152:155], v[32:33], off offset:3072
	global_load_dwordx4 v[156:159], v[34:35], off offset:3072

.LBB0_291:
	global_load_dwordx4 v[62:65], v[42:43], off offset:-3072
	global_load_dwordx4 v[74:77], v[42:43], off offset:-2048
	global_load_dwordx4 v[16:19], v[42:43], off
	global_load_dwordx4 v[20:23], v[42:43], off offset:-1024
	v_lshl_add_u64 v[48:49], s[10:11], 0, v[24:25]
	v_add_co_u32_e32 v48, vcc, s18, v48
	v_lshl_add_u64 v[56:57], s[8:9], 0, v[24:25]
	s_nop 0
	v_addc_co_u32_e32 v49, vcc, 0, v49, vcc
	s_waitcnt vmcnt(0)
	v_mov_b32_e32 v78, v112
	v_mov_b32_e32 v79, v113
	v_mov_b32_e32 v80, v114
	v_mov_b32_e32 v81, v115
	v_mov_b32_e32 v82, v116
	v_mov_b32_e32 v83, v117
	v_mov_b32_e32 v84, v118
	v_mov_b32_e32 v85, v119
	v_mov_b32_e32 v86, v120
	v_mov_b32_e32 v87, v121
	v_mov_b32_e32 v88, v122
	v_mov_b32_e32 v89, v123
	v_xor_b32_e32 v91, 0x80000000, v3
	v_xor_b32_e32 v90, 0x80000000, v2
	v_add_co_u32_e32 v54, vcc, s19, v56
	s_add_i32 s12, s12, 1
	s_nop 0
	v_addc_co_u32_e32 v55, vcc, 0, v57, vcc
	v_add_co_u32_e32 v56, vcc, s20, v56
	s_add_u32 s8, s8, 0x800
	s_nop 0
	v_addc_co_u32_e32 v57, vcc, 0, v57, vcc
	s_addc_u32 s9, s9, 0
	s_add_u32 s10, s10, 0x1000
	s_addc_u32 s11, s11, 0
	v_lshl_add_u64 v[42:43], v[42:43], 0, s[2:3]
	s_cmp_lt_i32 s12, s5
	v_pk_mul_f32 v[92:93], v[64:65], v[64:65]
	v_pk_mul_f32 v[94:95], v[62:63], v[62:63]
	v_pk_mul_f32 v[96:97], v[76:77], v[76:77]
	v_pk_mul_f32 v[98:99], v[74:75], v[74:75]
	v_pk_mov_b32 v[102:103], v[94:95], v[92:93] op_sel:[1,0]
	v_mov_b32_e32 v95, v93
	v_pk_mov_b32 v[92:93], v[98:99], v[96:97] op_sel:[1,0]
	v_mov_b32_e32 v99, v97
	v_mul_f32_e32 v66, v21, v21
	v_mul_f32_e32 v100, v23, v23
	v_pk_add_f32 v[94:95], v[102:103], v[94:95]
	v_pk_add_f32 v[92:93], v[92:93], v[98:99]
	v_mul_f32_e32 v104, v16, v16
	v_mul_f32_e32 v105, v17, v17
	v_mul_f32_e32 v106, v18, v18
	v_mul_f32_e32 v107, v19, v19
	v_pk_fma_f32 v[96:97], v[20:21], v[20:21], v[66:67] op_sel_hi:[1,1,0]
	v_pk_fma_f32 v[100:101], v[22:23], v[22:23], v[100:101] op_sel_hi:[1,1,0]
	v_pk_add_f32 v[94:95], v[94:95], v[94:95] op_sel:[0,1] op_sel_hi:[1,0]
	v_pk_add_f32 v[92:93], v[92:93], v[92:93] op_sel:[0,1] op_sel_hi:[1,0]
	v_mov_b32_e32 v97, v106
	v_mov_b32_e32 v101, v107
	v_mov_b32_e32 v95, v104
	v_mov_b32_e32 v93, v105
	v_pk_add_f32 v[96:97], v[96:97], v[100:101]
	v_pk_add_f32 v[92:93], v[94:95], v[92:93]
	s_nop 0
	v_pk_add_f32 v[92:93], v[92:93], v[96:97]
	s_nop 0
	v_add_f32_e32 v66, v92, v93
	ds_bpermute_b32 v92, v67, v66
	s_waitcnt lgkmcnt(0)
	v_add_f32_e32 v66, v66, v92
	ds_bpermute_b32 v92, v68, v66
	s_waitcnt lgkmcnt(0)
	v_add_f32_e32 v66, v66, v92
	ds_bpermute_b32 v92, v69, v66
	s_waitcnt lgkmcnt(0)
	v_add_f32_e32 v66, v66, v92
	ds_bpermute_b32 v92, v70, v66
	s_waitcnt lgkmcnt(0)
	v_add_f32_e32 v66, v66, v92
	ds_bpermute_b32 v92, v71, v66
	s_waitcnt lgkmcnt(0)
	v_add_f32_e32 v66, v66, v92
	ds_bpermute_b32 v92, v72, v66
	s_waitcnt lgkmcnt(0)
	v_add_f32_e32 v66, v66, v92
	v_fmamk_f32 v66, v66, 0x3a800000, v73
	v_rsq_f32_e32 v66, v66
	s_nop 0
	v_pk_mul_f32 v[94:95], v[62:63], v[66:67] op_sel_hi:[1,0]
	v_pk_mul_f32 v[92:93], v[64:65], v[66:67] op_sel_hi:[1,0]
	v_pk_mul_f32 v[64:65], v[0:1], v[94:95]
	v_pk_fma_f32 v[58:59], v[0:1], v[94:95], v[58:59] neg_lo:[1,0,0] neg_hi:[1,0,0]
	v_pk_mul_f32 v[62:63], v[2:3], v[92:93]
	v_pk_fma_f32 v[60:61], v[90:91], v[92:93], v[60:61]
	v_pk_fma_f32 v[78:79], v[78:79], v[58:59], v[64:65]
	v_pk_fma_f32 v[80:81], v[80:81], v[60:61], v[62:63]
	v_pk_fma_f32 v[82:83], v[82:83], v[58:59], v[64:65]
	v_pk_fma_f32 v[86:87], v[86:87], v[58:59], v[64:65]
	v_cvt_pk_bf16_f32 v78, v78, v79
	v_cvt_pk_bf16_f32 v79, v80, v81
	global_store_dwordx2 v[48:49], v[78:79], off
	v_cvt_pk_bf16_f32 v58, v58, v59
	v_cvt_pk_bf16_f32 v59, v60, v61
	v_pk_fma_f32 v[84:85], v[84:85], v[60:61], v[62:63]
	global_store_dwordx2 v[48:49], v[58:59], off offset:2048
	v_cvt_pk_bf16_f32 v58, v82, v83
	v_cvt_pk_bf16_f32 v59, v84, v85
	v_pk_fma_f32 v[88:89], v[88:89], v[60:61], v[62:63]
	global_store_dwordx2 v[54:55], v[58:59], off
	v_cvt_pk_bf16_f32 v58, v86, v87
	v_cvt_pk_bf16_f32 v59, v88, v89
	global_store_dwordx2 v[56:57], v[58:59], off
	s_nop 0
	v_pk_mul_f32 v[74:75], v[74:75], v[66:67] op_sel_hi:[1,0]
	v_xor_b32_e32 v87, 0x80000000, v7
	v_xor_b32_e32 v86, 0x80000000, v6
	v_pk_mul_f32 v[76:77], v[76:77], v[66:67] op_sel_hi:[1,0]
	v_pk_mul_f32 v[88:89], v[4:5], v[74:75]
	v_pk_fma_f32 v[50:51], v[4:5], v[74:75], v[50:51] neg_lo:[1,0,0] neg_hi:[1,0,0]
	v_pk_mul_f32 v[90:91], v[6:7], v[76:77]
	v_pk_fma_f32 v[52:53], v[86:87], v[76:77], v[52:53]
	v_pk_mul_f32 v[20:21], v[20:21], v[66:67] op_sel_hi:[1,0]
	v_pk_mul_f32 v[22:23], v[22:23], v[66:67] op_sel_hi:[1,0]
	v_pk_mul_f32 v[16:17], v[16:17], v[66:67] op_sel_hi:[1,0]
	v_pk_mul_f32 v[18:19], v[18:19], v[66:67] op_sel_hi:[1,0]
	v_pk_mul_f32 v[86:87], v[12:13], v[16:17]
	v_pk_fma_f32 v[16:17], v[12:13], v[16:17], v[38:39] neg_lo:[1,0,0] neg_hi:[1,0,0]
	v_pk_mul_f32 v[92:93], v[14:15], v[18:19]
	v_mov_b32_e32 v38, v86
	v_mov_b32_e32 v39, v87
	v_mov_b32_e32 v58, v124
	v_mov_b32_e32 v59, v125
	v_mov_b32_e32 v60, v126
	v_mov_b32_e32 v61, v127
	v_pk_fma_f32 v[58:59], v[50:51], v[58:59], v[88:89]
	v_pk_fma_f32 v[60:61], v[52:53], v[60:61], v[90:91]
	v_mov_b32_e32 v78, v128
	v_mov_b32_e32 v79, v129
	v_mov_b32_e32 v80, v130
	v_mov_b32_e32 v81, v131
	v_pk_fma_f32 v[74:75], v[52:53], v[80:81], v[90:91]
	v_pk_fma_f32 v[76:77], v[50:51], v[78:79], v[88:89]
	v_mov_b32_e32 v82, v132
	v_mov_b32_e32 v83, v133
	v_mov_b32_e32 v84, v134
	v_mov_b32_e32 v85, v135
	v_pk_fma_f32 v[80:81], v[50:51], v[82:83], v[88:89]
	v_cvt_pk_bf16_f32 v58, v58, v59
	v_cvt_pk_bf16_f32 v59, v60, v61
	global_store_dwordx2 v[48:49], v[58:59], off offset:512
	v_cvt_pk_bf16_f32 v50, v50, v51
	v_cvt_pk_bf16_f32 v51, v52, v53
	global_store_dwordx2 v[48:49], v[50:51], off offset:2560
	v_cvt_pk_bf16_f32 v50, v76, v77
	v_cvt_pk_bf16_f32 v51, v74, v75
	v_pk_fma_f32 v[78:79], v[52:53], v[84:85], v[90:91]
	global_store_dwordx2 v[54:55], v[50:51], off offset:512
	v_cvt_pk_bf16_f32 v50, v80, v81
	v_cvt_pk_bf16_f32 v51, v78, v79
	global_store_dwordx2 v[56:57], v[50:51], off offset:512
	s_nop 0
	v_xor_b32_e32 v79, 0x80000000, v11
	v_xor_b32_e32 v78, 0x80000000, v10
	v_pk_mul_f32 v[82:83], v[8:9], v[20:21]
	v_pk_fma_f32 v[20:21], v[8:9], v[20:21], v[44:45] neg_lo:[1,0,0] neg_hi:[1,0,0]
	v_pk_mul_f32 v[84:85], v[10:11], v[22:23]
	v_pk_fma_f32 v[22:23], v[78:79], v[22:23], v[46:47]
	v_mov_b32_e32 v50, v136
	v_mov_b32_e32 v51, v137
	v_mov_b32_e32 v52, v138
	v_mov_b32_e32 v53, v139
	v_pk_fma_f32 v[46:47], v[20:21], v[50:51], v[82:83]
	v_pk_fma_f32 v[44:45], v[22:23], v[52:53], v[84:85]
	v_mov_b32_e32 v58, v140
	v_mov_b32_e32 v59, v141
	v_mov_b32_e32 v60, v142
	v_mov_b32_e32 v61, v143
	v_pk_fma_f32 v[50:51], v[22:23], v[60:61], v[84:85]
	v_pk_fma_f32 v[52:53], v[20:21], v[58:59], v[82:83]
	v_mov_b32_e32 v74, v144
	v_mov_b32_e32 v75, v145
	v_mov_b32_e32 v76, v146
	v_mov_b32_e32 v77, v147
	v_pk_fma_f32 v[60:61], v[20:21], v[74:75], v[82:83]
	v_cvt_pk_bf16_f32 v46, v46, v47
	v_cvt_pk_bf16_f32 v47, v44, v45
	global_store_dwordx2 v[48:49], v[46:47], off offset:1024
	v_cvt_pk_bf16_f32 v20, v20, v21
	v_cvt_pk_bf16_f32 v21, v22, v23
	global_store_dwordx2 v[48:49], v[20:21], off offset:3072
	v_cvt_pk_bf16_f32 v20, v52, v53
	v_cvt_pk_bf16_f32 v21, v50, v51
	v_pk_fma_f32 v[58:59], v[22:23], v[76:77], v[84:85]
	global_store_dwordx2 v[54:55], v[20:21], off offset:1024
	v_cvt_pk_bf16_f32 v20, v60, v61
	v_cvt_pk_bf16_f32 v21, v58, v59
	global_store_dwordx2 v[56:57], v[20:21], off offset:1024
	s_nop 0
	v_xor_b32_e32 v45, 0x80000000, v15
	v_xor_b32_e32 v44, 0x80000000, v14
	v_pk_fma_f32 v[18:19], v[44:45], v[18:19], v[40:41]
	v_mov_b32_e32 v58, v64
	v_mov_b32_e32 v59, v65
	v_mov_b32_e32 v60, v62
	v_mov_b32_e32 v61, v63
	v_mov_b32_e32 v50, v88
	v_mov_b32_e32 v51, v89
	v_mov_b32_e32 v52, v90
	v_mov_b32_e32 v53, v91
	v_mov_b32_e32 v44, v82
	v_mov_b32_e32 v45, v83
	v_mov_b32_e32 v46, v84
	v_mov_b32_e32 v47, v85
	v_mov_b32_e32 v40, v92
	v_mov_b32_e32 v41, v93
	v_mov_b32_e32 v20, v148
	v_mov_b32_e32 v21, v149
	v_mov_b32_e32 v22, v150
	v_mov_b32_e32 v23, v151
	v_pk_fma_f32 v[20:21], v[16:17], v[20:21], v[86:87]
	v_pk_fma_f32 v[22:23], v[18:19], v[22:23], v[92:93]
	v_mov_b32_e32 v74, v152
	v_mov_b32_e32 v75, v153
	v_mov_b32_e32 v76, v154
	v_mov_b32_e32 v77, v155
	v_pk_fma_f32 v[62:63], v[18:19], v[76:77], v[92:93]
	v_pk_fma_f32 v[64:65], v[16:17], v[74:75], v[86:87]
	v_mov_b32_e32 v78, v156
	v_mov_b32_e32 v79, v157
	v_mov_b32_e32 v80, v158
	v_mov_b32_e32 v81, v159
	v_pk_fma_f32 v[76:77], v[16:17], v[78:79], v[86:87]
	v_cvt_pk_bf16_f32 v20, v20, v21
	v_cvt_pk_bf16_f32 v21, v22, v23
	global_store_dwordx2 v[48:49], v[20:21], off offset:1536
	v_cvt_pk_bf16_f32 v16, v16, v17
	v_cvt_pk_bf16_f32 v17, v18, v19
	global_store_dwordx2 v[48:49], v[16:17], off offset:3584
	v_cvt_pk_bf16_f32 v16, v64, v65
	v_cvt_pk_bf16_f32 v17, v62, v63
	v_pk_fma_f32 v[74:75], v[18:19], v[80:81], v[92:93]
	global_store_dwordx2 v[54:55], v[16:17], off offset:1536
	v_cvt_pk_bf16_f32 v16, v76, v77
	v_cvt_pk_bf16_f32 v17, v74, v75
	global_store_dwordx2 v[56:57], v[16:17], off offset:1536
	s_cbranch_scc1 .LBB0_291
	s_add_i32 s14, s14, s15
	s_add_i32 s16, s16, s17
	s_add_i32 s4, s4, s17
	s_cmpk_lt_i32 s14, 0x800
	s_cbranch_scc1 .LBB0_288
	s_load_dwordx2 s[2:3], s[0:1], 0x120
